# row-sum reductions in norm_rows/final_norm: xor16/xor32 butterfly steps via v_permlane16_swap/v_permlane32_swap instead of ds_bpermute
# speedup vs baseline: 1.0105x; 1.0042x over previous
; __device__ __forceinline__ float wave_sum(float v) {
; #pragma unroll
;     for (int o = 1; o < 64; o <<= 1) v += __shfl_xor(v, o);
;     return v;
; }
; __device__ __forceinline__ void norm_rows(const float* src, bf16_t* xn, float* outf, const float* gain, unsigned* rs_out, int tid, int bid, int nbk) {
;     ...
;     for (int m = gw; m < MTOK; m += NGW) {
;         const float* xr = src + (size_t)m * DM + lane * 8;
;         f32x4 v[4]; float s = 0.f;
; #pragma unroll
;         for (int j = 0; j < 4; ++j) { v[j] = *(const f32x4*)(xr + (j >> 1) * 512 + (j & 1) * 4); s += (v[j][0] * v[j][0] + v[j][1] * v[j][1]) + (v[j][2] * v[j][2] + v[j][3] * v[j][3]); }
;         const float tot = wave_sum(s);
;         if (rs_out && lane == 0) rs_out[m] = (unsigned)(tot * 1024.f + 0.5f);
.Lnr_body:
	v_mov_b32_e32 v8, v140
	v_mov_b32_e32 v9, v141
	v_mov_b32_e32 v10, v142
	v_mov_b32_e32 v11, v143
	v_mov_b32_e32 v4, v144
	v_mov_b32_e32 v5, v145
	v_mov_b32_e32 v6, v146
	v_mov_b32_e32 v7, v147
	v_mov_b32_e32 v16, v148
	v_mov_b32_e32 v17, v149
	v_mov_b32_e32 v18, v150
	v_mov_b32_e32 v19, v151
	v_mov_b32_e32 v12, v152
	v_mov_b32_e32 v13, v153
	v_mov_b32_e32 v14, v154
	v_mov_b32_e32 v15, v155
	v_add_u32_e32 v138, s44, v3
	v_cmp_ge_i32_e64 s[100:101], s67, v138
	s_and_saveexec_b64 s[100:101], s[100:101]
	v_lshl_add_u64 v[138:139], v[22:23], 0, s[48:49]
	global_load_dwordx4 v[140:143], v[138:139], off
	global_load_dwordx4 v[144:147], v[138:139], off offset:16
	global_load_dwordx4 v[148:151], v[138:139], off offset:2048
	global_load_dwordx4 v[152:155], v[138:139], off offset:2064
	s_mov_b64 exec, s[100:101]
	v_mul_f32_e32 v30, v9, v9
	s_waitcnt lgkmcnt(0)
	v_mul_f32_e32 v31, v11, v11
	v_mul_f32_e32 v32, v5, v5
	v_mul_f32_e32 v33, v7, v7
	v_mul_f32_e32 v34, v17, v17
	v_mul_f32_e32 v35, v19, v19
	v_fmac_f32_e32 v30, v8, v8
	v_fmac_f32_e32 v31, v10, v10
	v_fmac_f32_e32 v32, v4, v4
	v_fmac_f32_e32 v33, v6, v6
	v_mul_f32_e32 v36, v13, v13
	v_mul_f32_e32 v37, v15, v15
	v_fmac_f32_e32 v34, v16, v16
	v_fmac_f32_e32 v35, v18, v18
	v_add_f32_e32 v30, v30, v31
	v_add_f32_e32 v31, v32, v33
	v_fmac_f32_e32 v36, v12, v12
	v_fmac_f32_e32 v37, v14, v14
	v_add_f32_e32 v32, v34, v35
	v_add_f32_e32 v30, v30, v31
	v_add_f32_e32 v30, v30, v32
	v_add_f32_e32 v31, v36, v37
	v_add_f32_e32 v30, v30, v31
	s_waitcnt lgkmcnt(0)
	s_nop 1
	v_add_f32_dpp v30, v30, v30 quad_perm:[1,0,3,2] row_mask:0xf bank_mask:0xf
	s_waitcnt lgkmcnt(0)
	s_nop 1
	v_add_f32_dpp v30, v30, v30 quad_perm:[2,3,0,1] row_mask:0xf bank_mask:0xf
	s_waitcnt lgkmcnt(0)
	s_nop 1
	v_add_f32_dpp v30, v30, v30 row_half_mirror row_mask:0xf bank_mask:0xf
	s_waitcnt lgkmcnt(0)
	s_nop 1
	v_add_f32_dpp v30, v30, v30 row_mirror row_mask:0xf bank_mask:0xf
	v_mov_b32_e32 v31, v30
	s_nop 1
	v_permlane16_swap_b32_e32 v31, v30
	s_nop 1
	s_waitcnt lgkmcnt(0)
	v_add_f32_e32 v30, v30, v31
	v_mov_b32_e32 v31, v30
	s_nop 1
	v_permlane32_swap_b32_e32 v31, v30
	s_nop 1
	s_and_saveexec_b64 s[40:41], vcc
	s_cbranch_execz .LBB0_541
	s_waitcnt lgkmcnt(0)
	v_add_f32_e32 v30, v30, v31
	v_fma_f32 v30, v30, s3, 0.5
	v_cvt_u32_f32_e32 v30, v30
	global_store_dword v[0:1], v30, off
	s_branch .LBB0_541

; __device__ __forceinline__ float bflo(unsigned w) { return __uint_as_float(w << 16); }
; __device__ __forceinline__ float bfhi(unsigned w) { return __uint_as_float(w & 0xffff0000u); }
; __device__ __forceinline__ float wave_sum(float v) {
; #pragma unroll
;     for (int o = 1; o < 64; o <<= 1) v += __shfl_xor(v, o);
;     return v;
; }
; __device__ __forceinline__ void final_norm_rows(const bf16_t* xb, float* outf, const float* gain, int tid, int bid, int nbk) {
;     ...
;     for (int m = gw; m < MTOK; m += NGW) {
;         const bf16_t* xr = xb + (size_t)m * DM + lane * 8;
;         const u32x4 a = *(const u32x4*)xr, b = *(const u32x4*)(xr + 512);
;         float v[16];
;         v[0] = bflo(a.x); v[1] = bfhi(a.x); v[2] = bflo(a.y); v[3] = bfhi(a.y); v[4] = bflo(a.z); v[5] = bfhi(a.z); v[6] = bflo(a.w); v[7] = bfhi(a.w);
;         v[8] = bflo(b.x); v[9] = bfhi(b.x); v[10] = bflo(b.y); v[11] = bfhi(b.y); v[12] = bflo(b.z); v[13] = bfhi(b.z); v[14] = bflo(b.w); v[15] = bfhi(b.w);
;         float s = 0.f;
; #pragma unroll
;         for (int i = 0; i < 16; ++i) s += v[i] * v[i];
;         const float r = 1.0f / sqrtf(wave_sum(s) * (1.f / DM) + 1e-6f);
;         float* o = outf + (size_t)m * DM + lane * 8; const float* g = gain + lane * 8;
; #pragma unroll
;         for (int hh = 0; hh < 2; ++hh)
; #pragma unroll
;             for (int q = 0; q < 2; ++q) { const f32x4 gg = *(const f32x4*)(g + hh * 512 + q * 4); f32x4 ov; ov[0] = v[hh * 8 + q * 4 + 0] * r * gg[0]; ov[1] = v[hh * 8 + q * 4 + 1] * r * gg[1]; ov[2] = v[hh * 8 + q * 4 + 2] * r * gg[2]; ov[3] = v[hh * 8 + q * 4 + 3] * r * gg[3]; *(f32x4*)(o + hh * 512 + q * 4) = ov; }
.LBB0_547:
	s_waitcnt vmcnt(4)
	v_mov_b32_e32 v14, v204
	v_mov_b32_e32 v15, v205
	v_mov_b32_e32 v16, v206
	v_mov_b32_e32 v17, v207
	v_mov_b32_e32 v18, v208
	v_mov_b32_e32 v19, v209
	v_mov_b32_e32 v20, v210
	v_mov_b32_e32 v21, v211
	v_mov_b32_e32 v22, v188
	v_mov_b32_e32 v23, v189
	v_mov_b32_e32 v24, v190
	v_mov_b32_e32 v25, v191
	v_add_u32_e32 v3, s44, v3
	v_lshl_add_u64 v[4:5], v[4:5], 0, s[0:1]
	global_load_dwordx4 v[204:207], v[4:5], off
	global_load_dwordx4 v[208:211], v[4:5], off offset:1024
	v_lshlrev_b32_e32 v28, 16, v14
	v_and_b32_e32 v29, 0xffff0000, v14
	v_and_b32_e32 v26, 0xffff0000, v21
	v_lshlrev_b32_e32 v27, 16, v21
	v_lshlrev_b32_e32 v14, 16, v15
	v_and_b32_e32 v15, 0xffff0000, v15
	v_lshlrev_b32_e32 v36, 16, v20
	v_and_b32_e32 v37, 0xffff0000, v20
	v_pk_mul_f32 v[20:21], v[28:29], v[28:29]
	v_pk_mul_f32 v[38:39], v[14:15], v[14:15]
	v_add_f32_e32 v20, v20, v21
	v_lshlrev_b32_e32 v30, 16, v16
	v_and_b32_e32 v31, 0xffff0000, v16
	v_add_f32_e32 v20, v38, v20
	v_pk_mul_f32 v[40:41], v[30:31], v[30:31]
	v_add_f32_e32 v20, v39, v20
	v_lshlrev_b32_e32 v32, 16, v17
	v_and_b32_e32 v33, 0xffff0000, v17
	v_add_f32_e32 v20, v40, v20
	v_pk_mul_f32 v[42:43], v[32:33], v[32:33]
	v_add_f32_e32 v20, v41, v20
	v_lshlrev_b32_e32 v34, 16, v18
	v_and_b32_e32 v35, 0xffff0000, v18
	v_add_f32_e32 v20, v42, v20
	v_pk_mul_f32 v[44:45], v[34:35], v[34:35]
	v_add_f32_e32 v20, v43, v20
	v_lshlrev_b32_e32 v18, 16, v19
	v_and_b32_e32 v19, 0xffff0000, v19
	v_add_f32_e32 v20, v44, v20
	v_pk_mul_f32 v[46:47], v[18:19], v[18:19]
	v_add_f32_e32 v20, v45, v20
	v_add_f32_e32 v20, v46, v20
	v_pk_mul_f32 v[48:49], v[36:37], v[36:37]
	v_add_f32_e32 v20, v47, v20
	v_add_f32_e32 v20, v48, v20
	v_pk_mul_f32 v[16:17], v[26:27], v[26:27]
	v_add_f32_e32 v20, v49, v20
	v_add_f32_e32 v17, v17, v20
	v_add_f32_e32 v16, v16, v17
	s_waitcnt lgkmcnt(0)
	s_nop 1
	v_add_f32_dpp v16, v16, v16 quad_perm:[1,0,3,2] row_mask:0xf bank_mask:0xf
	s_waitcnt lgkmcnt(0)
	s_nop 1
	v_add_f32_dpp v16, v16, v16 quad_perm:[2,3,0,1] row_mask:0xf bank_mask:0xf
	s_waitcnt lgkmcnt(0)
	s_nop 1
	v_add_f32_dpp v16, v16, v16 row_half_mirror row_mask:0xf bank_mask:0xf
	s_waitcnt lgkmcnt(0)
	s_nop 1
	v_add_f32_dpp v16, v16, v16 row_mirror row_mask:0xf bank_mask:0xf
	v_mov_b32_e32 v17, v16
	s_nop 1
	v_permlane16_swap_b32_e32 v17, v16
	s_nop 1
	s_waitcnt lgkmcnt(0)
	v_add_f32_e32 v16, v16, v17
	v_mov_b32_e32 v17, v16
	s_nop 1
	v_permlane32_swap_b32_e32 v17, v16
	s_nop 1
	s_waitcnt lgkmcnt(0)
	v_add_f32_e32 v16, v16, v17
	v_fmamk_f32 v16, v16, 0x3a800000, v175
	v_mul_f32_e32 v17, 0x4f800000, v16
	v_cmp_gt_f32_e32 vcc, s33, v16
	s_nop 1
	v_cndmask_b32_e32 v16, v16, v17, vcc
	v_sqrt_f32_e32 v17, v16
	s_nop 0
	v_add_u32_e32 v20, -1, v17
	v_add_u32_e32 v21, 1, v17
	v_fma_f32 v38, -v20, v17, v16
	v_fma_f32 v39, -v21, v17, v16
	v_cmp_ge_f32_e64 s[40:41], 0, v38
	s_nop 1
	v_cndmask_b32_e64 v17, v17, v20, s[40:41]
	v_cmp_lt_f32_e64 s[40:41], 0, v39
	s_nop 1
	v_cndmask_b32_e64 v17, v17, v21, s[40:41]
	v_mul_f32_e32 v20, 0x37800000, v17
	v_cndmask_b32_e32 v17, v17, v20, vcc
	v_cmp_class_f32_e32 vcc, v16, v180
	s_nop 1
	v_cndmask_b32_e32 v16, v17, v16, vcc
	v_div_scale_f32 v17, s[10:11], v16, v16, 1.0
	v_rcp_f32_e32 v21, v17
	v_div_scale_f32 v20, vcc, 1.0, v16, 1.0
	v_fma_f32 v38, -v17, v21, 1.0
	v_fmac_f32_e32 v21, v38, v21
	v_mul_f32_e32 v38, v20, v21
	v_fma_f32 v39, -v17, v38, v20
	v_fmac_f32_e32 v38, v39, v21
	v_fma_f32 v17, -v17, v38, v20
	v_div_fmas_f32 v17, v17, v21, v38
	v_div_fixup_f32 v20, v17, v16, 1.0
	v_pk_mul_f32 v[28:29], v[20:21], v[28:29] op_sel_hi:[0,1]
	v_pk_mul_f32 v[14:15], v[20:21], v[14:15] op_sel_hi:[0,1]
	v_pk_mul_f32 v[16:17], v[24:25], v[14:15]
	v_pk_mul_f32 v[14:15], v[22:23], v[28:29]
	global_store_dwordx4 v[6:7], v[14:17], off
	s_nop 1
	v_mov_b32_e32 v14, v192
	v_mov_b32_e32 v15, v193
	v_mov_b32_e32 v16, v194
	v_mov_b32_e32 v17, v195
	v_pk_mul_f32 v[22:23], v[20:21], v[32:33] op_sel_hi:[0,1]
	v_pk_mul_f32 v[24:25], v[20:21], v[30:31] op_sel_hi:[0,1]
	v_pk_mul_f32 v[18:19], v[20:21], v[18:19] op_sel_hi:[0,1]
	v_cmp_lt_i32_e32 vcc, s67, v3
	s_or_b64 s[42:43], vcc, s[42:43]
	v_pk_mul_f32 v[14:15], v[14:15], v[24:25]
	v_pk_mul_f32 v[16:17], v[16:17], v[22:23]
	global_store_dwordx4 v[6:7], v[14:17], off offset:16
	s_nop 1
	v_mov_b32_e32 v14, v196
	v_mov_b32_e32 v15, v197
	v_mov_b32_e32 v16, v198
	v_mov_b32_e32 v17, v199
	v_pk_mul_f32 v[22:23], v[20:21], v[34:35] op_sel_hi:[0,1]
	v_pk_mul_f32 v[14:15], v[14:15], v[22:23]
	v_pk_mul_f32 v[16:17], v[16:17], v[18:19]
	global_store_dwordx4 v[6:7], v[14:17], off offset:2048
	s_nop 1
	v_mov_b32_e32 v14, v200
	v_mov_b32_e32 v15, v201
	v_mov_b32_e32 v16, v202
	v_mov_b32_e32 v17, v203
	v_pk_mul_f32 v[18:19], v[20:21], v[36:37] op_sel_hi:[0,1]
	v_pk_mul_f32 v[20:21], v[20:21], v[26:27] op_sel_hi:[0,1]
	v_pk_mul_f32 v[14:15], v[14:15], v[18:19]
	v_pk_mul_f32 v[16:17], v[16:17], v[20:21] op_sel:[0,1] op_sel_hi:[1,0]
	global_store_dwordx4 v[6:7], v[14:17], off offset:2064
	v_lshl_add_u64 v[6:7], v[6:7], 0, s[38:39]
	s_andn2_b64 exec, exec, s[42:43]
	s_cbranch_execnz .LBB0_547
